# N2: K/V LDS tile double-buffered, next tile written at end of step, one barrier per step (on top of v37)
# baseline (speedup 1.0000x reference)
; __device__ void phaseN2_task(const Params& p, int task, char* lds, bf16_t* ydst, int ystride, volatile unsigned* uex, char* ldsb) {
;     ...
;     {
;         const int lo = (t0 & ~31) - 511;
;         const int jb0 = lo > 0 ? (lo >> 6) : 0;
;         const int kkey = t512 >> 3, kch = (t512 & 7) * 8;
;         const int vd = t512 >> 3, vch = (t512 & 7) * 8;
;         const bf16_t* vtb = (const bf16_t*)(p.ws + OFF_VT) + ((size_t)(b * 2 + g) * 64 + vd) * SEQ + vch;
;         u32x4 kreg, vreg;
;         int br = 0, j = 0;
;         {
;             const bf16_t* kb = Z + (rowb + 0) * ZC + ZKS + g * 64;
;             kreg = *(const u32x4*)(kb + (size_t)kkey * ZC + kch);
;             vreg = *(const u32x4*)(vtb);
;         }
;         f32x4 O[2][4];
;         float m[2] = {-1e30f, -1e30f}, l[2] = {0.f, 0.f};
; #pragma unroll
;         for (int x = 0; x < 2; x++)
; #pragma unroll
;             for (int dt = 0; dt < 4; dt++) O[x][dt] = (f32x4){0.f, 0.f, 0.f, 0.f};
;         for (;;) {
;             __syncthreads();
;             *(u32x4*)(Ks + kkey * 64 + (((kch >> 3) ^ (kkey & 7)) * 8)) = kreg;
;             *(u32x4*)(VT + vd * 72 + vch) = vreg;
;             __syncthreads();
;             int nbr, nj;
;             if (br == 0) {
;                 const unsigned rem = (j >= 31) ? 0u : (uni & ~((2u << j) - 1u));
;                 if (rem) { nbr = 0; nj = __ffs((int)rem) - 1; } else { nbr = 1; nj = jb0; }
;             } else {
;                 if (j < cur) { nbr = 1; nj = j + 1; } else { nbr = 2; nj = 0; }
;             }
;             if (nbr < 2) {
;                 const bf16_t* kb = Z + (rowb + nj * 64) * ZC + (nbr ? ZKW : ZKS) + g * 64;
;                 kreg = *(const u32x4*)(kb + (size_t)kkey * ZC + kch);
;                 vreg = *(const u32x4*)(vtb + (size_t)nbr * (8 * 2 * 64) * SEQ + nj * 64);
;             }
.LBB0_616:
	s_or_b64 exec, exec, s[4:5]
	s_lshl_b32 s4, 2, s76
	s_add_i32 s4, s4, -1
	s_cmp_lg_u32 s76, 31
	s_cselect_b32 s10, s4, -2
	s_add_i32 s4, s1, 0xfffffe01
	s_ashr_i32 s11, s4, 6
	s_lshl_b32 s0, s0, 18
	s_add_u32 s4, s92, s0
	v_ashrrev_i32_e32 v49, 31, v48
	s_addc_u32 s5, s93, 0
	s_mul_i32 s0, s88, 0x2700
	v_lshlrev_b64 v[16:17], 12, v[48:49]
	s_add_u32 s0, s90, s0
	v_lshlrev_b32_e32 v25, 3, v124
	v_lshl_add_u64 v[16:17], s[4:5], 0, v[16:17]
	s_addc_u32 s5, s91, 0
	s_lshl_b32 s12, s89, 6
	s_lshl_b32 s4, s89, 7
	v_and_b32_e32 v34, 56, v25
	s_add_u32 s4, s0, s4
	s_movk_i32 s0, 0x1380
	v_lshlrev_b32_e32 v88, 1, v34
	s_addc_u32 s5, s5, 0
	v_mad_i64_i32 v[94:95], s[6:7], v48, s0, 0
	v_lshl_add_u64 v[36:37], v[16:17], 0, v[88:89]
	v_lshl_add_u64 v[16:17], v[94:95], 1, s[4:5]
	v_lshl_add_u64 v[16:17], v[16:17], 0, v[88:89]
	s_movk_i32 s0, 0x2000
	v_add_co_u32_e32 v16, vcc, s0, v16
	s_mov_b32 s0, 0xf800000
	s_nop 0
	v_addc_co_u32_e32 v17, vcc, 0, v17, vcc
	v_mov_b32_e32 v93, v91
	v_add_co_u32_e32 v20, vcc, s0, v36
	s_waitcnt lgkmcnt(0)
	s_barrier
	flat_load_dword v33, v[90:91] sc0 sc1
	s_waitcnt vmcnt(0)
	flat_load_dword v35, v[92:93] sc0 sc1
	s_waitcnt vmcnt(0)
	v_addc_co_u32_e32 v21, vcc, 0, v37, vcc
	global_load_dwordx4 v[16:19], v[16:17], off offset:512
	s_nop 0
	global_load_dwordx4 v[20:23], v[20:21], off
	v_and_b32_e32 v26, 7, v124
	v_lshlrev_b32_e32 v38, 7, v48
	v_bitop3_b32 v27, v75, v124, 7 bitop3:0x78
	v_bitop3_b32 v40, v25, 56, v124 bitop3:0x48
	v_bitop3_b32 v42, v75, v26, 4 bitop3:0x36
	v_lshlrev_b32_e32 v39, 4, v48
	v_lshlrev_b32_e32 v28, 4, v74
	v_lshlrev_b32_e32 v29, 1, v129
	v_mov_b32_e32 v24, 0
	v_lshlrev_b32_e32 v41, 4, v27
	v_lshl_or_b32 v136, v40, 1, v38
	v_lshlrev_b32_e32 v40, 4, v42
	s_mov_b64 s[4:5], 0xf800000
	s_cmpk_gt_i32 s1, 0x1ff
	s_mov_b32 s89, s85
	v_lshrrev_b32_e32 v93, 16, v127
	v_lshrrev_b32_e32 v133, 16, v128
	v_add_u32_e32 v134, 0xfffffe01, v126
	v_mov_b32_e32 v143, 0
	v_mov_b32_e32 v102, 0xf149f2ca
	s_mov_b64 s[8:9], 0
	v_mov_b32_e32 v103, 0xf149f2ca
	v_mov_b32_e32 v56, 0
	v_add3_u32 v135, v51, v28, v29
	v_mov_b32_e32 v25, v24
	v_mov_b32_e32 v26, v24
	v_mov_b32_e32 v27, v24
	v_mov_b32_e32 v28, v24
	v_mov_b32_e32 v29, v24
	v_mov_b32_e32 v30, v24
	v_mov_b32_e32 v31, v24
	v_mov_b32_e32 v32, v24
	v_lshlrev_b32_e32 v96, 1, v34
	v_add_u32_e32 v137, v51, v41
	v_add3_u32 v138, v38, v39, v88
	v_add_u32_e32 v139, v51, v40
	v_lshl_add_u64 v[98:99], v[36:37], 0, s[4:5]
	s_cselect_b32 s0, s11, 0
	s_lshl_b32 s84, s12, 1
	v_mov_b32_e32 v34, v24
	v_mov_b32_e32 v36, v24
	v_mov_b32_e32 v37, v24
	v_mov_b32_e32 v38, v24
	v_mov_b32_e32 v39, v24
	v_mov_b32_e32 v40, v24
	v_mov_b32_e32 v41, v24
	v_mov_b32_e32 v42, v24
	v_mov_b32_e32 v43, v24
	v_mov_b32_e32 v44, v24
	v_mov_b32_e32 v45, v24
	v_mov_b32_e32 v46, v24
	v_mov_b32_e32 v47, v24
	v_mov_b32_e32 v48, v24
	v_mov_b32_e32 v49, v24
	v_mov_b32_e32 v50, v24
	v_mov_b32_e32 v51, v24
	v_mov_b32_e32 v52, v24
	v_mov_b32_e32 v53, v24
	v_mov_b32_e32 v54, v24
	v_mov_b32_e32 v55, v24
	v_mov_b32_e32 v100, v24
	v_mov_b32_e32 v101, v24
	s_waitcnt lgkmcnt(0)
	v_bitop3_b32 v140, v35, s10, v33 bitop3:0xc8
	v_mov_b32_e32 v33, v24
	v_mov_b32_e32 v35, v24
	s_mov_b32 s22, 0
	s_waitcnt vmcnt(1)
	ds_write_b128 v136, v[16:19]
	s_waitcnt vmcnt(0)
	ds_write_b128 v138, v[20:23] offset:18432
	s_waitcnt lgkmcnt(0)
	s_branch .LBB0_618
.LBB0_617:
	s_or_b64 exec, exec, s[6:7]
	v_cmp_gt_u32_e64 s[6:7], 2, v141
	s_and_saveexec_b64 s[10:11], s[6:7]
	s_cbranch_execz .Ln2_nowrite
	s_waitcnt vmcnt(1)
	ds_write_b128 v219, v[16:19]
	s_waitcnt vmcnt(0)
	ds_write_b128 v220, v[20:23] offset:18432
	s_waitcnt lgkmcnt(0)
.Ln2_nowrite:
	s_or_b64 exec, exec, s[10:11]
	s_xor_b32 s22, s22, 0x12000
	v_cmp_eq_u32_e32 vcc, 2, v141
	s_or_b64 s[8:9], vcc, s[8:9]
	v_mov_b32_e32 v102, v97
	v_mov_b32_e32 v103, v88
	v_mov_b32_e32 v143, v141
	v_mov_b32_e32 v56, v142
	s_andn2_b64 exec, exec, s[8:9]
	s_cbranch_execz .LBB0_593
.LBB0_618:
	v_cmp_eq_u32_e64 s[4:5], 0, v143
	v_cmp_ne_u32_e32 vcc, 0, v143
	s_xor_b32 s23, s22, 0x12000
	v_add_u32_e32 v216, s22, v137
	v_add_u32_e32 v217, s22, v139
	v_add_u32_e32 v218, s22, v135
	v_add_u32_e32 v219, s23, v136
	v_add_u32_e32 v220, s23, v138
	s_barrier
	s_and_saveexec_b64 s[6:7], vcc
	s_xor_b64 s[10:11], exec, s[6:7]
	s_cbranch_execnz .LBB0_630
	s_andn2_saveexec_b64 s[10:11], s[10:11]
	s_cbranch_execnz .LBB0_631

; __device__ __forceinline__ f32x4 mfma16(bf16x8 a, bf16x8 b, f32x4 c) { return __builtin_amdgcn_mfma_f32_16x16x32_bf16(a, b, c, 0, 0, 0); }
; __device__ __forceinline__ void nsa_block_step(const bf16_t* Ks, const bf16_t* VT, const bf16x8 (&qf)[2][2], f32x4 (&O)[2][4], float (&m)[2], float (&l)[2],
;                                                int klo, int khi, int r, int q) {
;     f32x4 s[2][4];
; #pragma unroll
;     for (int x = 0; x < 2; x++)
; #pragma unroll
;         for (int kt = 0; kt < 4; kt++) s[x][kt] = (f32x4){0.f, 0.f, 0.f, 0.f};
; #pragma unroll
;     for (int kt = 0; kt < 4; kt++)
; #pragma unroll
;         for (int ks = 0; ks < 2; ks++) {
;             const bf16x8 kf = ld_frag(Ks + (kt * 16 + r) * 64 + (((ks * 4 + q) ^ (r & 7)) * 8));
; #pragma unroll
;             for (int x = 0; x < 2; x++) s[x][kt] = mfma16(kf, qf[x][ks], s[x][kt]);
;         }
;     if (!__all((klo <= 0) && (khi >= 63))) {
;         const int a = 4 * q - klo;
;         const unsigned range = (unsigned)(khi - klo);
;         const bool any = khi >= klo;
; #pragma unroll
;         for (int kt = 0; kt < 4; kt++)
; #pragma unroll
;             for (int j = 0; j < 4; j++) {
;                 const bool valid = any && ((unsigned)(kt * 16 + j + a) <= range);
; #pragma unroll
;                 for (int x = 0; x < 2; x++) s[x][kt][j] = valid ? s[x][kt][j] : -3.0e38f;
;             }
;     }
; __device__ void phaseN2_task(const Params& p, int task, char* lds, bf16_t* ydst, int ystride, volatile unsigned* uex, char* ldsb) {
;     ...
;             int klo = 0, khi = -1;
;             if (br == 0) { if ((mysel >> j) & 1u) khi = t - j * 64; }
;             else { khi = t - j * 64; klo = t - 511 - j * 64; }
;             klo = klo < 0 ? 0 : klo;
;             khi = khi > 63 ? 63 : khi;
.LBB0_622:
	s_or_b64 exec, exec, s[10:11]
	v_lshlrev_b32_e32 v57, 6, v56
	v_sub_u32_e32 v88, v126, v57
	s_and_saveexec_b64 s[6:7], vcc
	s_xor_b64 s[6:7], exec, s[6:7]
	v_sub_u32_e32 v56, v134, v57
	v_max_i32_e32 v97, 0, v56
	s_andn2_saveexec_b64 s[6:7], s[6:7]
	v_lshrrev_b32_e32 v56, v56, v132
	v_and_b32_e32 v56, 1, v56
	v_cmp_eq_u32_e32 vcc, 1, v56
	v_mov_b32_e32 v97, 0
	s_nop 0
	v_cndmask_b32_e32 v88, -1, v88, vcc
	s_or_b64 exec, exec, s[6:7]
	ds_read_b128 v[56:59], v216
	ds_read_b128 v[60:63], v216 offset:2048
	ds_read_b128 v[68:71], v217
	ds_read_b128 v[76:79], v217 offset:2048
	v_cmp_eq_u32_e32 vcc, 0, v97
	v_cmp_lt_i32_e64 s[6:7], 62, v88
	s_waitcnt lgkmcnt(3)
	v_mfma_f32_16x16x32_bf16 v[64:67], v[56:59], v[0:3], 0
	s_and_b64 s[6:7], vcc, s[6:7]
	v_mfma_f32_16x16x32_bf16 v[56:59], v[56:59], v[8:11], 0
	s_waitcnt lgkmcnt(1)
	v_mfma_f32_16x16x32_bf16 v[80:83], v[68:71], v[4:7], v[64:67]
	v_mfma_f32_16x16x32_bf16 v[68:71], v[68:71], v[12:15], v[56:59]
	v_mfma_f32_16x16x32_bf16 v[56:59], v[60:63], v[0:3], 0
	v_mfma_f32_16x16x32_bf16 v[60:63], v[60:63], v[8:11], 0
	s_waitcnt lgkmcnt(0)
	v_mfma_f32_16x16x32_bf16 v[72:75], v[76:79], v[4:7], v[56:59]
	v_mfma_f32_16x16x32_bf16 v[64:67], v[76:79], v[12:15], v[60:63]
	s_nop 3
	ds_read_b128 v[56:59], v216 offset:4096
	ds_read_b128 v[76:79], v216 offset:6144
	ds_read_b128 v[104:107], v217 offset:4096
	ds_read_b128 v[108:111], v217 offset:6144
	s_waitcnt lgkmcnt(3)
	v_mfma_f32_16x16x32_bf16 v[60:63], v[56:59], v[0:3], 0
	v_mfma_f32_16x16x32_bf16 v[56:59], v[56:59], v[8:11], 0
	s_waitcnt lgkmcnt(1)
	v_mfma_f32_16x16x32_bf16 v[84:87], v[104:107], v[4:7], v[60:63]
	v_mfma_f32_16x16x32_bf16 v[60:63], v[104:107], v[12:15], v[56:59]
	v_mfma_f32_16x16x32_bf16 v[56:59], v[76:79], v[0:3], 0
	v_mfma_f32_16x16x32_bf16 v[104:107], v[76:79], v[8:11], 0
	s_waitcnt lgkmcnt(0)
	v_mfma_f32_16x16x32_bf16 v[76:79], v[108:111], v[4:7], v[56:59]
	s_nop 4
	v_cndmask_b32_e64 v56, 0, 1, s[6:7]
	v_cmp_ne_u32_e32 vcc, 0, v56
	v_mfma_f32_16x16x32_bf16 v[56:59], v[108:111], v[12:15], v[104:107]
	s_cmp_eq_u64 vcc, exec
	s_cbranch_scc1 .LBB0_628
	v_min_i32_e32 v88, 63, v88
	v_sub_u32_e32 v104, v88, v97
	v_cmp_ge_i32_e32 vcc, v88, v97
	v_sub_u32_e32 v88, v129, v97
	v_cmp_le_u32_e64 s[6:7], v88, v104
	s_and_b64 s[6:7], vcc, s[6:7]
	v_add_u32_e32 v97, 1, v88
	v_cndmask_b32_e64 v80, v123, v80, s[6:7]
	v_cndmask_b32_e64 v68, v123, v68, s[6:7]
	v_cmp_le_u32_e64 s[6:7], v97, v104
	s_and_b64 s[6:7], vcc, s[6:7]
	v_add_u32_e32 v97, 2, v88
	v_cndmask_b32_e64 v81, v123, v81, s[6:7]
	v_cndmask_b32_e64 v69, v123, v69, s[6:7]
	v_cmp_le_u32_e64 s[6:7], v97, v104
	s_and_b64 s[6:7], vcc, s[6:7]
	v_add_u32_e32 v97, 3, v88
	v_cndmask_b32_e64 v82, v123, v82, s[6:7]
	v_cndmask_b32_e64 v70, v123, v70, s[6:7]
	v_cmp_le_u32_e64 s[6:7], v97, v104
	s_and_b64 s[6:7], vcc, s[6:7]
	v_add_u32_e32 v97, 16, v88
	v_cndmask_b32_e64 v83, v123, v83, s[6:7]
	v_cndmask_b32_e64 v71, v123, v71, s[6:7]
	v_cmp_le_u32_e64 s[6:7], v97, v104
	s_and_b64 s[6:7], vcc, s[6:7]
	v_add_u32_e32 v97, 17, v88
	v_cndmask_b32_e64 v72, v123, v72, s[6:7]
	v_cndmask_b32_e64 v64, v123, v64, s[6:7]
	v_cmp_le_u32_e64 s[6:7], v97, v104
	s_and_b64 s[6:7], vcc, s[6:7]
	v_add_u32_e32 v97, 18, v88
	v_cndmask_b32_e64 v73, v123, v73, s[6:7]
	v_cndmask_b32_e64 v65, v123, v65, s[6:7]
	v_cmp_le_u32_e64 s[6:7], v97, v104
	s_and_b64 s[6:7], vcc, s[6:7]
	v_add_u32_e32 v97, 19, v88
	v_cndmask_b32_e64 v74, v123, v74, s[6:7]
	v_cndmask_b32_e64 v66, v123, v66, s[6:7]
	v_cmp_le_u32_e64 s[6:7], v97, v104
	s_and_b64 s[6:7], vcc, s[6:7]
	v_add_u32_e32 v97, 32, v88
	v_cndmask_b32_e64 v75, v123, v75, s[6:7]
	v_cndmask_b32_e64 v67, v123, v67, s[6:7]
	v_cmp_le_u32_e64 s[6:7], v97, v104
	s_and_b64 s[6:7], vcc, s[6:7]
	v_add_u32_e32 v97, 33, v88
	v_cndmask_b32_e64 v84, v123, v84, s[6:7]
	v_cndmask_b32_e64 v60, v123, v60, s[6:7]
	v_cmp_le_u32_e64 s[6:7], v97, v104
	s_and_b64 s[6:7], vcc, s[6:7]
	v_add_u32_e32 v97, 34, v88
	v_cndmask_b32_e64 v85, v123, v85, s[6:7]
	v_cndmask_b32_e64 v61, v123, v61, s[6:7]
	v_cmp_le_u32_e64 s[6:7], v97, v104
	s_and_b64 s[6:7], vcc, s[6:7]
	v_add_u32_e32 v97, 35, v88
	v_cndmask_b32_e64 v86, v123, v86, s[6:7]
	v_cndmask_b32_e64 v62, v123, v62, s[6:7]
	v_cmp_le_u32_e64 s[6:7], v97, v104
	s_and_b64 s[6:7], vcc, s[6:7]
	v_add_u32_e32 v97, 48, v88
	v_cndmask_b32_e64 v87, v123, v87, s[6:7]
	v_cndmask_b32_e64 v63, v123, v63, s[6:7]
	v_cmp_le_u32_e64 s[6:7], v97, v104
	s_and_b64 s[6:7], vcc, s[6:7]
	v_add_u32_e32 v97, 49, v88
	v_cndmask_b32_e64 v76, v123, v76, s[6:7]
	v_cndmask_b32_e64 v56, v123, v56, s[6:7]
	v_cmp_le_u32_e64 s[6:7], v97, v104
	s_and_b64 s[6:7], vcc, s[6:7]
	v_add_u32_e32 v97, 50, v88
	v_cndmask_b32_e64 v77, v123, v77, s[6:7]
	v_cndmask_b32_e64 v57, v123, v57, s[6:7]
	v_cmp_le_u32_e64 s[6:7], v97, v104
	s_and_b64 s[6:7], vcc, s[6:7]
	v_add_u32_e32 v88, 51, v88
	v_cndmask_b32_e64 v78, v123, v78, s[6:7]
	v_cndmask_b32_e64 v58, v123, v58, s[6:7]
	v_cmp_le_u32_e64 s[6:7], v88, v104
	s_and_b64 vcc, vcc, s[6:7]
	v_cndmask_b32_e32 v79, v123, v79, vcc
	v_cndmask_b32_e32 v59, v123, v59, vcc
; __device__ __forceinline__ float exp2f_(float x) { return __builtin_amdgcn_exp2f(x); }
; __device__ __forceinline__ f32x4 mfma16(bf16x8 a, bf16x8 b, f32x4 c) { return __builtin_amdgcn_mfma_f32_16x16x32_bf16(a, b, c, 0, 0, 0); }
; __device__ __forceinline__ void nsa_block_step(const bf16_t* Ks, const bf16_t* VT, const bf16x8 (&qf)[2][2], f32x4 (&O)[2][4], float (&m)[2], float (&l)[2],
;                                                int klo, int khi, int r, int q) {
;     ...
;     bf16x8 pbv[2][2];
; #pragma unroll
;     for (int x = 0; x < 2; x++) {
;         float mx = fmaxf(fmaxf(fmaxf(s[x][0][0], s[x][0][1]), fmaxf(s[x][0][2], s[x][0][3])), fmaxf(fmaxf(s[x][1][0], s[x][1][1]), fmaxf(s[x][1][2], s[x][1][3])));
;         mx = fmaxf(mx, fmaxf(fmaxf(fmaxf(s[x][2][0], s[x][2][1]), fmaxf(s[x][2][2], s[x][2][3])), fmaxf(fmaxf(s[x][3][0], s[x][3][1]), fmaxf(s[x][3][2], s[x][3][3]))));
;         mx = xrow_max(mx);
;         const float mnew = fmaxf(m[x], mx);
;         const float alpha = exp2f_(m[x] - mnew);
;         m[x] = mnew;
;         float ls = 0.f;
; #pragma unroll
;         for (int kt = 0; kt < 4; kt++)
; #pragma unroll
;             for (int j = 0; j < 4; j++) { const float pv = exp2f_(s[x][kt][j] - mnew); s[x][kt][j] = pv; ls += pv; }
;         l[x] = l[x] * alpha + ls;
; #pragma unroll
;         for (int dt = 0; dt < 4; dt++) O[x][dt] *= alpha;
; #pragma unroll
;         for (int s2 = 0; s2 < 2; s2++) {
;             const u32x4 t4 = {pack2(s[x][2 * s2][0], s[x][2 * s2][1]), pack2(s[x][2 * s2][2], s[x][2 * s2][3]),
;                               pack2(s[x][2 * s2 + 1][0], s[x][2 * s2 + 1][1]), pack2(s[x][2 * s2 + 1][2], s[x][2 * s2 + 1][3])};
;             pbv[x][s2] = __builtin_bit_cast(bf16x8, t4);
;         }
;     }
; #pragma unroll
;     for (int s2 = 0; s2 < 2; s2++)
; #pragma unroll
;         for (int dt = 0; dt < 4; dt++) {
;             const u32x2 lo = *(const u32x2*)(VT + (dt * 16 + r) * 72 + (2 * s2) * 16 + 4 * q);
;             const u32x2 hi = *(const u32x2*)(VT + (dt * 16 + r) * 72 + (2 * s2 + 1) * 16 + 4 * q);
;             const bf16x8 va = mk_frag(lo, hi);
; #pragma unroll
;             for (int x = 0; x < 2; x++) O[x][dt] = mfma16(va, pbv[x][s2], O[x][dt]);
;         }
.LBB0_628:
	v_max3_f32 v88, v80, v81, v82
	v_max3_f32 v164, v68, v69, v70
	v_max3_f32 v97, v72, v73, v74
	v_max3_f32 v165, v64, v65, v66
	v_max3_f32 v104, v84, v85, v86
	v_max3_f32 v166, v60, v61, v62
	v_max3_f32 v105, v76, v77, v78
	v_max3_f32 v167, v56, v57, v58
	v_max3_f32 v88, v88, v83, v75
	v_max3_f32 v164, v164, v71, v67
	v_max3_f32 v97, v97, v87, v79
	v_max3_f32 v165, v165, v63, v59
	v_max3_f32 v88, v88, v97, v104
	v_max3_f32 v164, v164, v165, v166
	v_max_f32_e32 v88, v88, v105
	v_max_f32_e32 v164, v164, v167
	v_mov_b32_e32 v97, v88
	v_mov_b32_e32 v165, v164
	s_nop 0
	v_permlane16_swap_b32_e32 v88, v97
	s_nop 0
	v_permlane16_swap_b32_e32 v164, v165
	v_max_f32_e32 v88, v88, v97
	v_max_f32_e32 v164, v164, v165
	v_mov_b32_e32 v97, v88
	v_mov_b32_e32 v165, v164
	s_nop 0
	v_permlane32_swap_b32_e32 v88, v97
	s_nop 0
	v_permlane32_swap_b32_e32 v164, v165
	v_max3_f32 v88, v103, v88, v97
	v_sub_f32_e32 v72, v72, v88
	v_exp_f32_e32 v105, v72
	v_sub_f32_e32 v72, v73, v88
	v_exp_f32_e32 v109, v72
	v_sub_f32_e32 v72, v74, v88
	v_exp_f32_e32 v107, v72
	v_sub_f32_e32 v72, v75, v88
	v_sub_f32_e32 v80, v80, v88
	v_exp_f32_e32 v111, v72
	v_sub_f32_e32 v72, v84, v88
	v_exp_f32_e32 v117, v80
	v_sub_f32_e32 v80, v81, v88
	v_exp_f32_e32 v73, v72
	v_sub_f32_e32 v72, v85, v88
	v_exp_f32_e32 v113, v80
	v_sub_f32_e32 v80, v82, v88
	v_exp_f32_e32 v75, v72
	v_sub_f32_e32 v72, v86, v88
	v_exp_f32_e32 v115, v80
	v_sub_f32_e32 v80, v83, v88
	v_exp_f32_e32 v83, v72
	v_sub_f32_e32 v72, v87, v88
	v_exp_f32_e32 v81, v72
	v_sub_f32_e32 v72, v76, v88
	v_exp_f32_e32 v85, v72
	v_sub_f32_e32 v72, v77, v88
	v_exp_f32_e32 v87, v72
	v_sub_f32_e32 v72, v78, v88
	v_exp_f32_e32 v77, v72
	v_sub_f32_e32 v72, v79, v88
	v_exp_f32_e32 v79, v72
	v_sub_f32_e32 v97, v103, v88
	v_exp_f32_e32 v103, v80
	v_exp_f32_e32 v76, v97
	v_max3_f32 v97, v102, v164, v165
	v_sub_f32_e32 v64, v64, v97
	v_sub_f32_e32 v68, v68, v97
	v_exp_f32_e32 v104, v64
	v_sub_f32_e32 v64, v65, v97
	v_sub_f32_e32 v78, v102, v97
	v_exp_f32_e32 v116, v68
	v_sub_f32_e32 v68, v69, v97
	v_exp_f32_e32 v108, v64
	v_sub_f32_e32 v64, v66, v97
	v_exp_f32_e32 v112, v68
	v_exp_f32_e32 v106, v64
	v_sub_f32_e32 v64, v67, v97
	v_sub_f32_e32 v60, v60, v97
	v_exp_f32_e32 v160, v78
	v_add_u32_e32 v78, 0x4800, v218
	v_exp_f32_e32 v110, v64
	v_exp_f32_e32 v72, v60
	v_sub_f32_e32 v60, v61, v97
	ds_read2_b64 v[64:67], v78 offset1:4
	v_exp_f32_e32 v74, v60
	v_sub_f32_e32 v60, v62, v97
	v_sub_f32_e32 v68, v70, v97
	v_exp_f32_e32 v82, v60
	v_sub_f32_e32 v60, v63, v97
	v_exp_f32_e32 v114, v68
	v_sub_f32_e32 v68, v71, v97
	v_pk_add_f32 v[156:157], v[116:117], 0 op_sel_hi:[1,0]
	v_exp_f32_e32 v80, v60
	v_cvt_pk_bf16_f32 v60, v116, v112
	v_add_u32_e32 v116, 0x5000, v218
	v_exp_f32_e32 v102, v68
	ds_read2_b64 v[68:71], v116 offset0:32 offset1:36
	v_mov_b32_e32 v161, v76
	v_pk_mul_f32 v[146:147], v[54:55], v[76:77] op_sel_hi:[1,0]
	v_pk_mul_f32 v[144:145], v[52:53], v[76:77] op_sel_hi:[1,0]
	v_cvt_pk_bf16_f32 v52, v117, v113
	v_cvt_pk_bf16_f32 v53, v115, v103
	v_cvt_pk_bf16_f32 v54, v105, v109
	v_cvt_pk_bf16_f32 v55, v107, v111
	v_pk_mul_f32 v[38:39], v[38:39], v[160:161] op_sel_hi:[1,0]
	v_pk_mul_f32 v[36:37], v[36:37], v[160:161] op_sel_hi:[1,0]
	v_cvt_pk_bf16_f32 v61, v114, v102
	v_cvt_pk_bf16_f32 v62, v104, v108
	v_cvt_pk_bf16_f32 v63, v106, v110
	v_add_u32_e32 v117, 0x5800, v218
	s_waitcnt lgkmcnt(1)
	v_mfma_f32_16x16x32_bf16 v[144:147], v[64:67], v[52:55], v[144:147]
	v_mul_f32_e64 v150, v50, v76
	v_mul_f32_e64 v151, v51, v76
	v_pk_mul_f32 v[148:149], v[48:49], v[76:77] op_sel_hi:[1,0]
	v_pk_mul_f32 v[34:35], v[34:35], v[160:161] op_sel_hi:[1,0]
	v_mfma_f32_16x16x32_bf16 v[36:39], v[64:67], v[60:63], v[36:39]
	ds_read2_b64 v[64:67], v117 offset0:64 offset1:68
	v_pk_mul_f32 v[32:33], v[32:33], v[160:161] op_sel_hi:[1,0]
	v_add_u32_e32 v162, 0x6000, v218
	s_waitcnt lgkmcnt(1)
	v_mfma_f32_16x16x32_bf16 v[148:151], v[68:71], v[52:55], v[148:151]
	v_mul_f32_e64 v50, v46, v76
	v_mul_f32_e64 v51, v47, v76
	v_pk_mul_f32 v[48:49], v[44:45], v[76:77] op_sel_hi:[1,0]
	v_pk_mul_f32 v[46:47], v[42:43], v[76:77] op_sel_hi:[1,0]
	v_mfma_f32_16x16x32_bf16 v[32:35], v[68:71], v[60:63], v[32:35]
	ds_read2_b64 v[68:71], v162 offset0:96 offset1:100
	v_pk_mul_f32 v[44:45], v[40:41], v[76:77] op_sel_hi:[1,0]
	v_sub_f32_e32 v56, v56, v97
	s_waitcnt lgkmcnt(1)
	v_mfma_f32_16x16x32_bf16 v[152:155], v[64:67], v[52:55], v[48:51]
	v_mul_f32_e64 v30, v30, v160
	v_mul_f32_e64 v31, v31, v160
	v_pk_mul_f32 v[28:29], v[28:29], v[160:161] op_sel_hi:[1,0]
	v_exp_f32_e32 v84, v56
	v_sub_f32_e32 v48, v58, v97
	v_exp_f32_e32 v76, v48
	ds_read2_b64 v[48:51], v78 offset0:8 offset1:12
	v_sub_f32_e32 v56, v57, v97
	v_mfma_f32_16x16x32_bf16 v[28:31], v[64:67], v[60:63], v[28:31]
	v_exp_f32_e32 v86, v56
	v_cvt_pk_bf16_f32 v40, v73, v75
	v_cvt_pk_bf16_f32 v41, v83, v81
	s_waitcnt lgkmcnt(1)
	v_mfma_f32_16x16x32_bf16 v[64:67], v[68:71], v[52:55], v[44:47]
	v_cvt_pk_bf16_f32 v42, v85, v87
	v_cvt_pk_bf16_f32 v43, v77, v79
	v_cvt_pk_bf16_f32 v56, v72, v74
	v_sub_f32_e32 v44, v59, v97
	v_exp_f32_e32 v78, v44
	ds_read2_b64 v[44:47], v116 offset0:40 offset1:44
	v_cvt_pk_bf16_f32 v57, v82, v80
	v_cvt_pk_bf16_f32 v58, v84, v86
	v_cvt_pk_bf16_f32 v59, v76, v78
	v_pk_mul_f32 v[26:27], v[26:27], v[160:161] op_sel_hi:[1,0]
	v_pk_mul_f32 v[24:25], v[24:25], v[160:161] op_sel_hi:[1,0]
	s_waitcnt lgkmcnt(1)
	v_mfma_f32_16x16x32_bf16 v[52:55], v[48:51], v[40:43], v[144:147]
	v_cmp_ne_u32_e32 vcc, v141, v143
	v_mfma_f32_16x16x32_bf16 v[36:39], v[48:51], v[56:59], v[36:39]
	v_add_f32_e64 v48, v112, v156
	v_add_f32_e64 v49, v113, v157
	v_mfma_f32_16x16x32_bf16 v[24:27], v[68:71], v[60:63], v[24:27]
	v_add_f32_e64 v68, v114, v48
	v_add_f32_e64 v69, v115, v49
	ds_read2_b64 v[60:63], v117 offset0:72 offset1:76
	v_pk_add_f32 v[68:69], v[102:103], v[68:69]
	s_waitcnt lgkmcnt(1)
; __device__ __forceinline__ float sigmoidf_(float x) { return __builtin_amdgcn_rcpf(1.f + __expf(-x)); }
; __device__ __forceinline__ f32x4 mfma16(bf16x8 a, bf16x8 b, f32x4 c) { return __builtin_amdgcn_mfma_f32_16x16x32_bf16(a, b, c, 0, 0, 0); }
; __device__ __forceinline__ void nsa_block_step(const bf16_t* Ks, const bf16_t* VT, const bf16x8 (&qf)[2][2], f32x4 (&O)[2][4], float (&m)[2], float (&l)[2],
;                                                int klo, int khi, int r, int q) {
;     ...
; #pragma unroll
;     for (int s2 = 0; s2 < 2; s2++)
; #pragma unroll
;         for (int dt = 0; dt < 4; dt++) {
;             const u32x2 lo = *(const u32x2*)(VT + (dt * 16 + r) * 72 + (2 * s2) * 16 + 4 * q);
;             const u32x2 hi = *(const u32x2*)(VT + (dt * 16 + r) * 72 + (2 * s2 + 1) * 16 + 4 * q);
;             const bf16x8 va = mk_frag(lo, hi);
; #pragma unroll
;             for (int x = 0; x < 2; x++) O[x][dt] = mfma16(va, pbv[x][s2], O[x][dt]);
;         }
; __device__ void phaseN2_task(const Params& p, int task, char* lds, bf16_t* ydst, int ystride, volatile unsigned* uex, char* ldsb) {
;     ...
;             if (nbr != br) {
; #pragma unroll
;                 for (int x = 0; x < 2; x++) {
;                     float lt = l[x];
;                     lt = xrow_sum(lt);
;                     const float sc = sigmoidf_(br == 0 ? gatev[1][x] : gatev[2][x]) / lt;
; #pragma unroll
;                     for (int dt = 0; dt < 4; dt++) { ofl[(wave * 8 + x * 4 + dt) * 64 + lane] += sc * O[x][dt]; O[x][dt] = (f32x4){0.f, 0.f, 0.f, 0.f}; }
;                     m[x] = -1e30f; l[x] = 0.f;
;                 }
;             }
	v_mfma_f32_16x16x32_bf16 v[48:51], v[44:47], v[40:43], v[148:151]
	v_add_f32_e64 v68, v104, v68
	v_add_f32_e64 v69, v105, v69
	v_pk_add_f32 v[68:69], v[108:109], v[68:69]
	v_mfma_f32_16x16x32_bf16 v[32:35], v[44:47], v[56:59], v[32:35]
	v_add_f32_e64 v44, v106, v68
	v_add_f32_e64 v45, v107, v69
	ds_read2_b64 v[68:71], v162 offset0:104 offset1:108
	v_pk_add_f32 v[102:103], v[110:111], v[44:45]
	s_waitcnt lgkmcnt(1)
	v_mfma_f32_16x16x32_bf16 v[44:47], v[60:63], v[40:43], v[152:155]
	v_add_f32_e64 v72, v72, v102
	v_add_f32_e64 v73, v73, v103
	v_pk_add_f32 v[72:73], v[74:75], v[72:73]
	v_mfma_f32_16x16x32_bf16 v[28:31], v[60:63], v[56:59], v[28:31]
	v_add_f32_e64 v72, v82, v72
	v_add_f32_e64 v73, v83, v73
	v_pk_add_f32 v[60:61], v[80:81], v[72:73]
	s_waitcnt lgkmcnt(0)
	v_mfma_f32_16x16x32_bf16 v[40:43], v[68:71], v[40:43], v[64:67]
	v_add_f32_e64 v60, v84, v60
	v_add_f32_e64 v61, v85, v61
	v_pk_add_f32 v[60:61], v[86:87], v[60:61]
	v_mfma_f32_16x16x32_bf16 v[24:27], v[68:71], v[56:59], v[24:27]
	v_add_f32_e64 v60, v76, v60
	v_add_f32_e64 v61, v77, v61
	v_pk_add_f32 v[60:61], v[78:79], v[60:61]
	s_nop 0
	v_pk_fma_f32 v[100:101], v[100:101], v[160:161], v[60:61]
	s_and_saveexec_b64 s[6:7], vcc
	s_cbranch_execz .LBB0_617
	s_mov_b64 vcc, s[4:5]
	v_cndmask_b32_sdwa v57, v128, v127, vcc dst_sel:WORD_1 dst_unused:UNUSED_PAD src0_sel:DWORD src1_sel:DWORD
	v_mov_b32_e32 v56, v101
	v_mul_f32_e32 v57, 0xbfb8aa3b, v57
	v_exp_f32_e32 v57, v57
	v_permlane16_swap_b32_e32 v101, v56
	v_add_f32_e32 v56, v101, v56
	v_add_f32_e32 v57, 1.0, v57
	v_rcp_f32_e32 v60, v57
	v_mov_b32_e32 v58, v56
	s_nop 1
	v_permlane32_swap_b32_e32 v56, v58
	v_add_f32_e32 v61, v56, v58
	v_div_scale_f32 v56, s[10:11], v61, v61, v60
	v_rcp_f32_e32 v62, v56
	v_mov_b32_e32 v97, 0xf149f2ca
	v_mov_b32_e32 v88, 0xf149f2ca
	v_fma_f32 v57, -v56, v62, 1.0
	v_fmac_f32_e32 v62, v57, v62
	v_div_scale_f32 v57, vcc, v60, v61, v60
	v_mul_f32_e32 v63, v57, v62
	v_fma_f32 v58, -v56, v63, v57
	v_fmac_f32_e32 v63, v58, v62
	v_fma_f32 v64, -v56, v63, v57
	ds_read_b128 v[56:59], v131 offset:35840
	v_div_fmas_f32 v62, v64, v62, v63
	v_div_fixup_f32 v64, v62, v61, v60
	ds_read_b128 v[60:63], v131 offset:36864
	s_waitcnt lgkmcnt(1)
	v_pk_fma_f32 v[54:55], v[54:55], v[64:65], v[58:59] op_sel_hi:[1,0,1]
	v_pk_fma_f32 v[52:53], v[52:53], v[64:65], v[56:57] op_sel_hi:[1,0,1]
	ds_write_b128 v131, v[52:55] offset:35840
	ds_read_b128 v[52:55], v131 offset:37888
	s_waitcnt lgkmcnt(2)
	v_pk_fma_f32 v[50:51], v[50:51], v[64:65], v[62:63] op_sel_hi:[1,0,1]
	v_pk_fma_f32 v[48:49], v[48:49], v[64:65], v[60:61] op_sel_hi:[1,0,1]
	ds_write_b128 v131, v[48:51] offset:36864
	ds_read_b128 v[48:51], v131 offset:38912
	s_waitcnt lgkmcnt(2)
	v_pk_fma_f32 v[46:47], v[46:47], v[64:65], v[54:55] op_sel_hi:[1,0,1]
	v_pk_fma_f32 v[44:45], v[44:45], v[64:65], v[52:53] op_sel_hi:[1,0,1]
	ds_write_b128 v131, v[44:47] offset:37888
	v_cndmask_b32_e64 v45, v133, v93, s[4:5]
	v_lshlrev_b32_e32 v45, 16, v45
	v_mul_f32_e32 v45, 0xbfb8aa3b, v45
	v_exp_f32_e32 v45, v45
	v_mov_b32_e32 v44, v100
	s_nop 1
	v_permlane16_swap_b32_e32 v100, v44
	v_add_f32_e32 v45, 1.0, v45
	v_add_f32_e32 v44, v100, v44
	v_rcp_f32_e32 v45, v45
	v_mov_b32_e32 v46, v44
	s_nop 1
	v_permlane32_swap_b32_e32 v44, v46
	v_add_f32_e32 v44, v44, v46
	v_div_scale_f32 v46, s[4:5], v44, v44, v45
	v_rcp_f32_e32 v47, v46
	s_waitcnt lgkmcnt(1)
	v_pk_fma_f32 v[42:43], v[42:43], v[64:65], v[50:51] op_sel_hi:[1,0,1]
	v_pk_fma_f32 v[40:41], v[40:41], v[64:65], v[48:49] op_sel_hi:[1,0,1]
	ds_write_b128 v131, v[40:43] offset:38912
	v_fma_f32 v40, -v46, v47, 1.0
	v_fmac_f32_e32 v47, v40, v47
	v_div_scale_f32 v40, vcc, v45, v44, v45
	v_mul_f32_e32 v48, v40, v47
	v_fma_f32 v41, -v46, v48, v40
	v_fmac_f32_e32 v48, v41, v47
	v_fma_f32 v46, -v46, v48, v40
	ds_read_b128 v[40:43], v131 offset:39936
	v_div_fmas_f32 v46, v46, v47, v48
	v_div_fixup_f32 v48, v46, v44, v45
	ds_read_b128 v[44:47], v131 offset:40960
	s_waitcnt lgkmcnt(1)
	v_pk_fma_f32 v[38:39], v[38:39], v[48:49], v[42:43] op_sel_hi:[1,0,1]
	v_pk_fma_f32 v[36:37], v[36:37], v[48:49], v[40:41] op_sel_hi:[1,0,1]
	ds_write_b128 v131, v[36:39] offset:39936
	ds_read_b128 v[36:39], v131 offset:41984
	ds_read_b128 v[40:43], v131 offset:43008
	s_waitcnt lgkmcnt(3)
	v_pk_fma_f32 v[34:35], v[34:35], v[48:49], v[46:47] op_sel_hi:[1,0,1]
	v_pk_fma_f32 v[32:33], v[32:33], v[48:49], v[44:45] op_sel_hi:[1,0,1]
	ds_write_b128 v131, v[32:35] offset:40960
	s_waitcnt lgkmcnt(2)
	v_pk_fma_f32 v[30:31], v[30:31], v[48:49], v[38:39] op_sel_hi:[1,0,1]
	s_waitcnt lgkmcnt(1)
	v_pk_fma_f32 v[26:27], v[26:27], v[48:49], v[42:43] op_sel_hi:[1,0,1]
	v_pk_fma_f32 v[24:25], v[24:25], v[48:49], v[40:41] op_sel_hi:[1,0,1]
	v_pk_fma_f32 v[28:29], v[28:29], v[48:49], v[36:37] op_sel_hi:[1,0,1]
	ds_write_b128 v131, v[24:27] offset:43008
	v_mov_b32_e32 v24, 0
	ds_write_b128 v131, v[28:31] offset:41984
	v_mov_b32_e32 v25, v24
	v_mov_b32_e32 v26, v24
	v_mov_b32_e32 v27, v24
	v_mov_b32_e32 v28, v24
	v_mov_b32_e32 v29, v24
	v_mov_b32_e32 v30, v24
	v_mov_b32_e32 v31, v24
	v_mov_b32_e32 v32, v24
	v_mov_b32_e32 v33, v24
	v_mov_b32_e32 v34, v24
	v_mov_b32_e32 v35, v24
	v_mov_b32_e32 v36, v24
	v_mov_b32_e32 v37, v24
	v_mov_b32_e32 v38, v24
	v_mov_b32_e32 v39, v24
	v_mov_b32_e32 v40, v24
	v_mov_b32_e32 v41, v24
	v_mov_b32_e32 v42, v24
	v_mov_b32_e32 v43, v24
	v_mov_b32_e32 v44, v24
	v_mov_b32_e32 v45, v24
	v_mov_b32_e32 v46, v24
	v_mov_b32_e32 v47, v24
	v_mov_b32_e32 v48, v24
	v_mov_b32_e32 v49, v24
	v_mov_b32_e32 v50, v24
	v_mov_b32_e32 v51, v24
	v_mov_b32_e32 v52, v24
	v_mov_b32_e32 v53, v24
	v_mov_b32_e32 v54, v24
	v_mov_b32_e32 v55, v24
	v_mov_b32_e32 v100, v24
	v_mov_b32_e32 v101, v24
	s_branch .LBB0_617
